# select_row exact path: 32 membership bits per lane in one cmp/addc chain, 8x8 nibble transpose per 8-lane group (DPP + bfi), one 64-lane mask store per row
# speedup vs baseline: 1.0035x; 1.0006x over previous
; DI void select_row(const float* SC, unsigned* dmask, int b, int t, int lane) {
;     ...
;     const unsigned long long ltmask = (1ull << lane) - 1ull;
; #pragma unroll
;     for (int k = 0; k < 8; ++k) {
;         unsigned nib = 0u;
;         if (k < nch) {
;             if (exact) {
; #pragma unroll
;                 for (int e = 0; e < 4; ++e) nib |= (u[k][e] >= T ? 1u : 0u) << e;
;             } else {
;                 unsigned long long bm[4]; int lanes_before = 0, tot = 0;
; #pragma unroll
;                 for (int e = 0; e < 4; ++e) { bm[e] = __ballot(u[k][e] == T); lanes_before += __popcll(bm[e] & ltmask); tot += __popcll(bm[e]); }
;                 int rank = tie_before + lanes_before;
; #pragma unroll
;                 for (int e = 0; e < 4; ++e) { const bool eq = (u[k][e] == T); const bool s = (u[k][e] > T) || (eq && rank < need); nib |= (s ? 1u : 0u) << e; rank += eq ? 1 : 0; }
;                 tie_before += tot;
;             }
;         }
;         unsigned val = nib << (4 * (lane & 7));
;         val |= (unsigned)__builtin_amdgcn_update_dpp(0, (int)val, 0x101, 0xf, 0xf, true); val |= (unsigned)__builtin_amdgcn_update_dpp(0, (int)val, 0x102, 0xf, 0xf, true); val |= (unsigned)__builtin_amdgcn_update_dpp(0, (int)val, 0x104, 0xf, 0xf, true);
;         if ((lane & 7) == 0) dm[8 * k + (lane >> 3)] = val;
.LBB0_599:
	s_mov_b32 s92, s57
	s_and_b64 vcc, exec, s[88:89]
	s_cbranch_vccz .Lsel_slow
	s_load_dwordx4 s[88:91], s[0:1], 0x0
	v_cmp_le_u32_e32 vcc, v2, v17
	v_addc_co_u32_e32 v1, vcc, 0, v43, vcc
	v_cmp_le_u32_e32 vcc, v2, v12
	v_addc_co_u32_e32 v1, vcc, v1, v1, vcc
	v_cmp_le_u32_e32 vcc, v2, v14
	v_addc_co_u32_e32 v1, vcc, v1, v1, vcc
	v_cmp_le_u32_e32 vcc, v2, v13
	v_addc_co_u32_e32 v1, vcc, v1, v1, vcc
	v_cmp_le_u32_e32 vcc, v2, v20
	v_addc_co_u32_e32 v1, vcc, v1, v1, vcc
	v_cmp_le_u32_e32 vcc, v2, v19
	v_addc_co_u32_e32 v1, vcc, v1, v1, vcc
	v_cmp_le_u32_e32 vcc, v2, v16
	v_addc_co_u32_e32 v1, vcc, v1, v1, vcc
	v_cmp_le_u32_e32 vcc, v2, v15
	v_addc_co_u32_e32 v1, vcc, v1, v1, vcc
	v_cmp_le_u32_e32 vcc, v2, v23
	v_addc_co_u32_e32 v1, vcc, v1, v1, vcc
	v_cmp_le_u32_e32 vcc, v2, v18
	v_addc_co_u32_e32 v1, vcc, v1, v1, vcc
	v_cmp_le_u32_e32 vcc, v2, v22
	v_addc_co_u32_e32 v1, vcc, v1, v1, vcc
	v_cmp_le_u32_e32 vcc, v2, v21
	v_addc_co_u32_e32 v1, vcc, v1, v1, vcc
	v_cmp_le_u32_e32 vcc, v2, v27
	v_addc_co_u32_e32 v1, vcc, v1, v1, vcc
	v_cmp_le_u32_e32 vcc, v2, v26
	v_addc_co_u32_e32 v1, vcc, v1, v1, vcc
	v_cmp_le_u32_e32 vcc, v2, v25
	v_addc_co_u32_e32 v1, vcc, v1, v1, vcc
	v_cmp_le_u32_e32 vcc, v2, v24
	v_addc_co_u32_e32 v1, vcc, v1, v1, vcc
	v_cmp_le_u32_e32 vcc, v2, v31
	v_addc_co_u32_e32 v1, vcc, v1, v1, vcc
	v_cmp_le_u32_e32 vcc, v2, v28
	v_addc_co_u32_e32 v1, vcc, v1, v1, vcc
	v_cmp_le_u32_e32 vcc, v2, v30
	v_addc_co_u32_e32 v1, vcc, v1, v1, vcc
	v_cmp_le_u32_e32 vcc, v2, v29
	v_addc_co_u32_e32 v1, vcc, v1, v1, vcc
	v_cmp_le_u32_e32 vcc, v2, v42
	v_addc_co_u32_e32 v1, vcc, v1, v1, vcc
	v_cmp_le_u32_e32 vcc, v2, v32
	v_addc_co_u32_e32 v1, vcc, v1, v1, vcc
	v_cmp_le_u32_e32 vcc, v2, v41
	v_addc_co_u32_e32 v1, vcc, v1, v1, vcc
	v_cmp_le_u32_e32 vcc, v2, v33
	v_addc_co_u32_e32 v1, vcc, v1, v1, vcc
	v_cmp_le_u32_e32 vcc, v2, v5
	v_addc_co_u32_e32 v1, vcc, v1, v1, vcc
	v_cmp_le_u32_e32 vcc, v2, v8
	v_addc_co_u32_e32 v1, vcc, v1, v1, vcc
	v_cmp_le_u32_e32 vcc, v2, v6
	v_addc_co_u32_e32 v1, vcc, v1, v1, vcc
	v_cmp_le_u32_e32 vcc, v2, v7
	v_addc_co_u32_e32 v1, vcc, v1, v1, vcc
	v_cmp_le_u32_e32 vcc, v2, v9
	v_addc_co_u32_e32 v1, vcc, v1, v1, vcc
	v_cmp_le_u32_e32 vcc, v2, v121
	v_addc_co_u32_e32 v1, vcc, v1, v1, vcc
	v_cmp_le_u32_e32 vcc, v2, v10
	v_addc_co_u32_e32 v1, vcc, v1, v1, vcc
	v_cmp_le_u32_e32 vcc, v2, v11
	v_addc_co_u32_e32 v1, vcc, v1, v1, vcc
	s_mov_b32 s10, 0xf0f0f0f0
	s_mov_b32 s11, 0xf0f0f0f0
	s_mov_b32 s80, 0xcccccccc
	s_mov_b32 s81, 0xcccccccc
	s_mov_b32 s84, 0xaaaaaaaa
	s_mov_b32 s85, 0xaaaaaaaa
	s_mov_b32 s86, 0xffff
	s_mov_b32 s87, 0xff00ff
	s_mov_b32 s93, 0xf0f0f0f
	s_nop 1
	v_mov_b32_dpp v3, v1 row_shl:4 row_mask:0xf bank_mask:0xf bound_ctrl:1
	v_mov_b32_dpp v4, v1 row_shr:4 row_mask:0xf bank_mask:0xf bound_ctrl:1
	v_cndmask_b32_e64 v3, v3, v4, s[10:11]
	v_lshrrev_b32_e32 v34, 16, v3
	v_lshlrev_b32_e32 v35, 16, v3
	v_cndmask_b32_e64 v34, v1, v34, s[10:11]
	v_cndmask_b32_e64 v35, v35, v1, s[10:11]
	v_bfi_b32 v1, s86, v34, v35
	s_nop 1
	v_mov_b32_dpp v3, v1 quad_perm:[2,3,0,1] row_mask:0xf bank_mask:0xf
	v_lshrrev_b32_e32 v34, 8, v3
	v_lshlrev_b32_e32 v35, 8, v3
	v_cndmask_b32_e64 v34, v1, v34, s[80:81]
	v_cndmask_b32_e64 v35, v35, v1, s[80:81]
	v_bfi_b32 v1, s87, v34, v35
	s_nop 1
	v_mov_b32_dpp v3, v1 quad_perm:[1,0,3,2] row_mask:0xf bank_mask:0xf
	v_lshrrev_b32_e32 v34, 4, v3
	v_lshlrev_b32_e32 v35, 4, v3
	v_cndmask_b32_e64 v34, v1, v34, s[84:85]
	v_cndmask_b32_e64 v35, v35, v1, s[84:85]
	v_bfi_b32 v1, s93, v34, v35
	v_lshlrev_b32_e32 v3, 2, v132
	v_lshl_add_u32 v3, v241, 3, v3
	global_store_dword v3, v1, s[48:49]
	s_waitcnt lgkmcnt(0)
	s_mov_b64 s[8:9], 0
	s_branch .LBB0_657
.Lsel_slow:
	s_andn2_b64 vcc, exec, s[8:9]
	s_cbranch_vccnz .LBB0_601
	s_mov_b32 s90, 0
	v_cmp_le_u32_e32 vcc, v2, v9
	v_addc_co_u32_e32 v1, vcc, 0, v43, vcc
	v_cmp_le_u32_e32 vcc, v2, v121
	v_addc_co_u32_e32 v1, vcc, v1, v1, vcc
	v_cmp_le_u32_e32 vcc, v2, v10
	v_addc_co_u32_e32 v1, vcc, v1, v1, vcc
	v_cmp_le_u32_e32 vcc, v2, v11
	v_addc_co_u32_e32 v1, vcc, v1, v1, vcc
